# EpiUp: hoist the 8 ssq loads ahead of the stores (one vmcnt wait per tile instead of 8)
# baseline (speedup 1.0000x reference)
; DEVI u32x4 pack8(const f32x4 a, const f32x4 b) { u32x4 w; w.x = cvtpk(a[0], a[1]); w.y = cvtpk(a[2], a[3]); w.z = cvtpk(b[0], b[1]); w.w = cvtpk(b[2], b[3]); return w; }
; DEVI unsigned char* WSP() { return *(unsigned char* const __attribute__((address_space(4)))*)(kargs() + 8 * 22); }
; #define ROWLOOP _Pragma("unroll") for (int ai = 0; ai < 2; ++ai) _Pragma("unroll") for (int m = 0; m < 4; ++m)
;     DEVI void operator()(AccRef acc, const Unit& u, int wr, int wc, int fr, int fq) const {
;         unsigned char* ws = WSP();
;         const float* ssq = (const float*)(ws + O_SSQZ) + (size_t)(1 + l) * MT; bf16_t* ah = (bf16_t*)(ws + O_AH);
;         ROWLOOP {
;             const int row = ROWOF(u);
;             const float r = rsqrtf(ssq[row] * (1.f / 1024.f) + EPSF);
; #pragma unroll
;             for (int bj = 0; bj < 2; ++bj) {
;                 f32x4 a = acc[ai][bj][m][0] * r, b = acc[ai][bj][m][1] * r;
; #pragma unroll
;                 for (int j = 0; j < 4; ++j) { const float x = fmaxf(a[j], 0.f), y = fmaxf(b[j], 0.f); a[j] = x * x; b[j] = y * y; }
;                 *(u32x4*)(ah + (size_t)row * DFF + u.pn * 256 + bj * 128 + wc * 32 + 8 * fq) = pack8(a, b);
;             }
;         }
;     }
.LBB0_1623:
	s_mov_b64 s[52:53], s[0:1]
	v_mbcnt_lo_u32_b32 v0, -1, 0
	v_mbcnt_hi_u32_b32 v0, -1, v0
	v_lshl_or_b32 v0, s33, 6, v0
	s_load_dwordx2 s[52:53], s[52:53], 0xb0
	v_readfirstlane_b32 s11, v0
	s_mov_b64 s[56:57], 0x28990800
	s_waitcnt lgkmcnt(0)
	s_add_u32 s54, s52, s12
	s_addc_u32 s55, s53, 0
	s_ashr_i32 s47, s11, 2
	s_lshl_b32 s4, s4, 8
	s_andn2_b32 s47, s47, 63
	s_add_i32 s47, s47, s4
	v_and_or_b32 v142, v0, 15, s47
	v_ashrrev_i32_e32 v143, 31, v142
	v_lshl_add_u64 v[144:145], v[142:143], 2, s[54:55]
	s_mov_b32 s4, 0xa5000
	v_add_co_u32_e32 v146, vcc, s4, v144
	s_mov_b64 s[54:55], 0xa5000
	s_nop 0
	v_addc_co_u32_e32 v147, vcc, 0, v145, vcc
	global_load_dword v152, v[146:147], off
	global_load_dword v156, v[146:147], off offset:64
	global_load_dword v157, v[146:147], off offset:128
	global_load_dword v158, v[146:147], off offset:192
	global_load_dword v159, v[146:147], off offset:512
	global_load_dword v160, v[146:147], off offset:576
	global_load_dword v161, v[146:147], off offset:640
	global_load_dword v162, v[146:147], off offset:704
	s_lshl_b32 s4, s5, 8
	v_lshlrev_b64 v[150:151], 13, v[142:143]
	s_ashr_i32 s5, s4, 31
	v_lshl_add_u64 v[146:147], v[144:145], 0, s[54:55]
	s_lshl_b64 s[4:5], s[4:5], 1
	s_add_u32 s4, s52, s4
	s_addc_u32 s5, s53, s5
	s_and_b32 s11, s11, 0xc0
	s_add_u32 s4, s4, s11
	v_and_b32_e32 v0, 48, v0
	s_addc_u32 s5, s5, 0
	s_waitcnt vmcnt(0)
	v_fmamk_f32 v143, v152, 0x3a800000, v233
	v_mul_f32_e32 v144, 0x4b800000, v143
	v_cmp_gt_f32_e32 vcc, s25, v143
	s_nop 1
	v_cndmask_b32_e32 v143, v143, v144, vcc
	v_rsq_f32_e32 v143, v143
	v_lshl_add_u64 v[144:145], s[4:5], 0, v[0:1]
	v_lshl_add_u64 v[144:145], v[144:145], 0, s[56:57]
	v_lshl_add_u64 v[150:151], v[144:145], 0, v[150:151]
	v_mul_f32_e32 v0, 0x45800000, v143
	v_cndmask_b32_e32 v0, v143, v0, vcc
	v_pk_mul_f32 v[128:129], v[128:129], v[0:1] op_sel_hi:[1,0]
	v_pk_mul_f32 v[126:127], v[126:127], v[0:1] op_sel_hi:[1,0]
	v_pk_mul_f32 v[124:125], v[124:125], v[0:1] op_sel_hi:[1,0]
	v_pk_mul_f32 v[122:123], v[122:123], v[0:1] op_sel_hi:[1,0]
	v_pk_mul_f32 v[120:121], v[120:121], v[0:1] op_sel_hi:[1,0]
	v_pk_mul_f32 v[118:119], v[118:119], v[0:1] op_sel_hi:[1,0]
	v_pk_mul_f32 v[116:117], v[116:117], v[0:1] op_sel_hi:[1,0]
	v_pk_mul_f32 v[114:115], v[114:115], v[0:1] op_sel_hi:[1,0]
	v_max_f32_e32 v126, 0, v126
	v_max_f32_e32 v122, 0, v122
	v_max_f32_e32 v127, 0, v127
	v_max_f32_e32 v123, 0, v123
	v_max_f32_e32 v128, 0, v128
	v_max_f32_e32 v124, 0, v124
	v_max_f32_e32 v129, 0, v129
	v_max_f32_e32 v125, 0, v125
	v_max_f32_e32 v118, 0, v118
	v_max_f32_e32 v114, 0, v114
	v_max_f32_e32 v119, 0, v119
	v_max_f32_e32 v115, 0, v115
	v_max_f32_e32 v120, 0, v120
	v_max_f32_e32 v116, 0, v116
	v_max_f32_e32 v121, 0, v121
	v_max_f32_e32 v117, 0, v117
	v_pk_mul_f32 v[126:127], v[126:127], v[126:127]
	v_pk_mul_f32 v[122:123], v[122:123], v[122:123]
	v_pk_mul_f32 v[128:129], v[128:129], v[128:129]
	v_pk_mul_f32 v[124:125], v[124:125], v[124:125]
	v_pk_mul_f32 v[118:119], v[118:119], v[118:119]
	v_pk_mul_f32 v[152:153], v[114:115], v[114:115]
	v_pk_mul_f32 v[120:121], v[120:121], v[120:121]
	v_pk_mul_f32 v[154:155], v[116:117], v[116:117]
	v_cvt_pk_bf16_f32 v114, v126, v127
	v_cvt_pk_bf16_f32 v115, v128, v129
	v_cvt_pk_bf16_f32 v116, v122, v123
	v_cvt_pk_bf16_f32 v117, v124, v125
	v_cvt_pk_bf16_f32 v118, v118, v119
	v_cvt_pk_bf16_f32 v119, v120, v121
	v_cvt_pk_bf16_f32 v120, v152, v153
	v_cvt_pk_bf16_f32 v121, v154, v155
	global_store_dwordx4 v[150:151], v[114:117], off
	global_store_dwordx4 v[150:151], v[118:121], off offset:256
	s_nop 0
	v_or_b32_e32 v114, 16, v142
	v_fmamk_f32 v0, v156, 0x3a800000, v233
	v_mul_f32_e32 v115, 0x4b800000, v0
	v_cmp_gt_f32_e32 vcc, s25, v0
	s_nop 1
	v_cndmask_b32_e32 v0, v0, v115, vcc
	v_rsq_f32_e32 v0, v0
	v_ashrrev_i32_e32 v115, 31, v114
	v_lshlrev_b64 v[114:115], 13, v[114:115]
	v_lshl_add_u64 v[114:115], v[144:145], 0, v[114:115]
	v_mul_f32_e32 v116, 0x45800000, v0
	v_cndmask_b32_e32 v0, v0, v116, vcc
	v_pk_mul_f32 v[112:113], v[112:113], v[0:1] op_sel_hi:[1,0]
	v_pk_mul_f32 v[110:111], v[110:111], v[0:1] op_sel_hi:[1,0]
	v_pk_mul_f32 v[108:109], v[108:109], v[0:1] op_sel_hi:[1,0]
	v_pk_mul_f32 v[106:107], v[106:107], v[0:1] op_sel_hi:[1,0]
	v_pk_mul_f32 v[104:105], v[104:105], v[0:1] op_sel_hi:[1,0]
	v_pk_mul_f32 v[102:103], v[102:103], v[0:1] op_sel_hi:[1,0]
	v_pk_mul_f32 v[100:101], v[100:101], v[0:1] op_sel_hi:[1,0]
	v_pk_mul_f32 v[98:99], v[98:99], v[0:1] op_sel_hi:[1,0]
	v_max_f32_e32 v110, 0, v110
	v_max_f32_e32 v106, 0, v106
	v_max_f32_e32 v111, 0, v111
	v_max_f32_e32 v107, 0, v107
	v_max_f32_e32 v112, 0, v112
	v_max_f32_e32 v108, 0, v108
	v_max_f32_e32 v113, 0, v113
	v_max_f32_e32 v109, 0, v109
	v_max_f32_e32 v102, 0, v102
	v_max_f32_e32 v98, 0, v98
	v_max_f32_e32 v103, 0, v103
	v_max_f32_e32 v99, 0, v99
	v_max_f32_e32 v104, 0, v104
	v_max_f32_e32 v100, 0, v100
	v_max_f32_e32 v105, 0, v105
	v_max_f32_e32 v101, 0, v101
	v_pk_mul_f32 v[110:111], v[110:111], v[110:111]
	v_pk_mul_f32 v[106:107], v[106:107], v[106:107]
	v_pk_mul_f32 v[112:113], v[112:113], v[112:113]
	v_pk_mul_f32 v[108:109], v[108:109], v[108:109]
	v_pk_mul_f32 v[102:103], v[102:103], v[102:103]
	v_pk_mul_f32 v[116:117], v[98:99], v[98:99]
	v_pk_mul_f32 v[104:105], v[104:105], v[104:105]
	v_pk_mul_f32 v[118:119], v[100:101], v[100:101]
	v_cvt_pk_bf16_f32 v98, v110, v111
	v_cvt_pk_bf16_f32 v99, v112, v113
	v_cvt_pk_bf16_f32 v100, v106, v107
	v_cvt_pk_bf16_f32 v101, v108, v109
	v_cvt_pk_bf16_f32 v102, v102, v103
	v_cvt_pk_bf16_f32 v103, v104, v105
	v_cvt_pk_bf16_f32 v104, v116, v117
	v_cvt_pk_bf16_f32 v105, v118, v119
	global_store_dwordx4 v[114:115], v[98:101], off
; DEVI u32x4 pack8(const f32x4 a, const f32x4 b) { u32x4 w; w.x = cvtpk(a[0], a[1]); w.y = cvtpk(a[2], a[3]); w.z = cvtpk(b[0], b[1]); w.w = cvtpk(b[2], b[3]); return w; }
; #define ROWLOOP _Pragma("unroll") for (int ai = 0; ai < 2; ++ai) _Pragma("unroll") for (int m = 0; m < 4; ++m)
;     DEVI void operator()(AccRef acc, const Unit& u, int wr, int wc, int fr, int fq) const {
;     ...
;         ROWLOOP {
;             const int row = ROWOF(u);
;             const float r = rsqrtf(ssq[row] * (1.f / 1024.f) + EPSF);
; #pragma unroll
;             for (int bj = 0; bj < 2; ++bj) {
;                 f32x4 a = acc[ai][bj][m][0] * r, b = acc[ai][bj][m][1] * r;
; #pragma unroll
;                 for (int j = 0; j < 4; ++j) { const float x = fmaxf(a[j], 0.f), y = fmaxf(b[j], 0.f); a[j] = x * x; b[j] = y * y; }
;                 *(u32x4*)(ah + (size_t)row * DFF + u.pn * 256 + bj * 128 + wc * 32 + 8 * fq) = pack8(a, b);
;             }
;         }
	global_store_dwordx4 v[114:115], v[102:105], off offset:256
	s_nop 0
	v_or_b32_e32 v98, 32, v142
	v_fmamk_f32 v0, v157, 0x3a800000, v233
	v_mul_f32_e32 v99, 0x4b800000, v0
	v_cmp_gt_f32_e32 vcc, s25, v0
	s_nop 1
	v_cndmask_b32_e32 v0, v0, v99, vcc
	v_rsq_f32_e32 v0, v0
	v_ashrrev_i32_e32 v99, 31, v98
	v_lshlrev_b64 v[98:99], 13, v[98:99]
	v_lshl_add_u64 v[98:99], v[144:145], 0, v[98:99]
	v_mul_f32_e32 v100, 0x45800000, v0
	v_cndmask_b32_e32 v0, v0, v100, vcc
	v_pk_mul_f32 v[96:97], v[96:97], v[0:1] op_sel_hi:[1,0]
	v_pk_mul_f32 v[94:95], v[94:95], v[0:1] op_sel_hi:[1,0]
	v_pk_mul_f32 v[92:93], v[92:93], v[0:1] op_sel_hi:[1,0]
	v_pk_mul_f32 v[90:91], v[90:91], v[0:1] op_sel_hi:[1,0]
	v_pk_mul_f32 v[88:89], v[88:89], v[0:1] op_sel_hi:[1,0]
	v_pk_mul_f32 v[86:87], v[86:87], v[0:1] op_sel_hi:[1,0]
	v_pk_mul_f32 v[84:85], v[84:85], v[0:1] op_sel_hi:[1,0]
	v_pk_mul_f32 v[82:83], v[82:83], v[0:1] op_sel_hi:[1,0]
	v_max_f32_e32 v94, 0, v94
	v_max_f32_e32 v90, 0, v90
	v_max_f32_e32 v95, 0, v95
	v_max_f32_e32 v91, 0, v91
	v_max_f32_e32 v96, 0, v96
	v_max_f32_e32 v92, 0, v92
	v_max_f32_e32 v97, 0, v97
	v_max_f32_e32 v93, 0, v93
	v_max_f32_e32 v86, 0, v86
	v_max_f32_e32 v82, 0, v82
	v_max_f32_e32 v87, 0, v87
	v_max_f32_e32 v83, 0, v83
	v_max_f32_e32 v88, 0, v88
	v_max_f32_e32 v84, 0, v84
	v_max_f32_e32 v89, 0, v89
	v_max_f32_e32 v85, 0, v85
	v_pk_mul_f32 v[94:95], v[94:95], v[94:95]
	v_pk_mul_f32 v[90:91], v[90:91], v[90:91]
	v_pk_mul_f32 v[96:97], v[96:97], v[96:97]
	v_pk_mul_f32 v[92:93], v[92:93], v[92:93]
	v_pk_mul_f32 v[86:87], v[86:87], v[86:87]
	v_pk_mul_f32 v[100:101], v[82:83], v[82:83]
	v_pk_mul_f32 v[88:89], v[88:89], v[88:89]
	v_pk_mul_f32 v[102:103], v[84:85], v[84:85]
	v_cvt_pk_bf16_f32 v82, v94, v95
	v_cvt_pk_bf16_f32 v83, v96, v97
	v_cvt_pk_bf16_f32 v84, v90, v91
	v_cvt_pk_bf16_f32 v85, v92, v93
	v_cvt_pk_bf16_f32 v86, v86, v87
	v_cvt_pk_bf16_f32 v87, v88, v89
	v_cvt_pk_bf16_f32 v88, v100, v101
	v_cvt_pk_bf16_f32 v89, v102, v103
	global_store_dwordx4 v[98:99], v[82:85], off
	global_store_dwordx4 v[98:99], v[86:89], off offset:256
	s_nop 0
	v_or_b32_e32 v82, 48, v142
	v_fmamk_f32 v0, v158, 0x3a800000, v233
	v_mul_f32_e32 v83, 0x4b800000, v0
	v_cmp_gt_f32_e32 vcc, s25, v0
	s_nop 1
	v_cndmask_b32_e32 v0, v0, v83, vcc
	v_rsq_f32_e32 v0, v0
	v_ashrrev_i32_e32 v83, 31, v82
	v_lshlrev_b64 v[82:83], 13, v[82:83]
	v_lshl_add_u64 v[82:83], v[144:145], 0, v[82:83]
	v_mul_f32_e32 v84, 0x45800000, v0
	v_cndmask_b32_e32 v0, v0, v84, vcc
	v_pk_mul_f32 v[80:81], v[80:81], v[0:1] op_sel_hi:[1,0]
	v_pk_mul_f32 v[78:79], v[78:79], v[0:1] op_sel_hi:[1,0]
	v_pk_mul_f32 v[76:77], v[76:77], v[0:1] op_sel_hi:[1,0]
	v_pk_mul_f32 v[74:75], v[74:75], v[0:1] op_sel_hi:[1,0]
	v_pk_mul_f32 v[72:73], v[72:73], v[0:1] op_sel_hi:[1,0]
	v_pk_mul_f32 v[70:71], v[70:71], v[0:1] op_sel_hi:[1,0]
	v_pk_mul_f32 v[68:69], v[68:69], v[0:1] op_sel_hi:[1,0]
	v_pk_mul_f32 v[66:67], v[66:67], v[0:1] op_sel_hi:[1,0]
	v_max_f32_e32 v78, 0, v78
	v_max_f32_e32 v74, 0, v74
	v_max_f32_e32 v79, 0, v79
	v_max_f32_e32 v75, 0, v75
	v_max_f32_e32 v80, 0, v80
	v_max_f32_e32 v76, 0, v76
	v_max_f32_e32 v81, 0, v81
	v_max_f32_e32 v77, 0, v77
	v_max_f32_e32 v70, 0, v70
	v_max_f32_e32 v66, 0, v66
	v_max_f32_e32 v71, 0, v71
	v_max_f32_e32 v67, 0, v67
	v_max_f32_e32 v72, 0, v72
	v_max_f32_e32 v68, 0, v68
	v_max_f32_e32 v73, 0, v73
	v_max_f32_e32 v69, 0, v69
	v_pk_mul_f32 v[78:79], v[78:79], v[78:79]
	v_pk_mul_f32 v[74:75], v[74:75], v[74:75]
	v_pk_mul_f32 v[80:81], v[80:81], v[80:81]
	v_pk_mul_f32 v[76:77], v[76:77], v[76:77]
	v_pk_mul_f32 v[70:71], v[70:71], v[70:71]
	v_pk_mul_f32 v[84:85], v[66:67], v[66:67]
	v_pk_mul_f32 v[72:73], v[72:73], v[72:73]
	v_pk_mul_f32 v[86:87], v[68:69], v[68:69]
	v_cvt_pk_bf16_f32 v66, v78, v79
	v_cvt_pk_bf16_f32 v67, v80, v81
	v_cvt_pk_bf16_f32 v68, v74, v75
	v_cvt_pk_bf16_f32 v69, v76, v77
	v_cvt_pk_bf16_f32 v70, v70, v71
	v_cvt_pk_bf16_f32 v71, v72, v73
	v_cvt_pk_bf16_f32 v72, v84, v85
	v_cvt_pk_bf16_f32 v73, v86, v87
	global_store_dwordx4 v[82:83], v[66:69], off
	global_store_dwordx4 v[82:83], v[70:73], off offset:256
	s_nop 0
	v_add_u32_e32 v66, 0x80, v142
	v_fmamk_f32 v0, v159, 0x3a800000, v233
	v_mul_f32_e32 v67, 0x4b800000, v0
	v_cmp_gt_f32_e32 vcc, s25, v0
	s_nop 1
	v_cndmask_b32_e32 v0, v0, v67, vcc
	v_rsq_f32_e32 v0, v0
	v_ashrrev_i32_e32 v67, 31, v66
	v_lshlrev_b64 v[66:67], 13, v[66:67]
	v_lshl_add_u64 v[66:67], v[144:145], 0, v[66:67]
	v_mul_f32_e32 v68, 0x45800000, v0
	v_cndmask_b32_e32 v0, v0, v68, vcc
	v_pk_mul_f32 v[64:65], v[64:65], v[0:1] op_sel_hi:[1,0]
	v_pk_mul_f32 v[62:63], v[62:63], v[0:1] op_sel_hi:[1,0]
	v_pk_mul_f32 v[60:61], v[60:61], v[0:1] op_sel_hi:[1,0]
	v_pk_mul_f32 v[58:59], v[58:59], v[0:1] op_sel_hi:[1,0]
	v_pk_mul_f32 v[56:57], v[56:57], v[0:1] op_sel_hi:[1,0]
	v_pk_mul_f32 v[54:55], v[54:55], v[0:1] op_sel_hi:[1,0]
	v_pk_mul_f32 v[52:53], v[52:53], v[0:1] op_sel_hi:[1,0]
	v_pk_mul_f32 v[50:51], v[50:51], v[0:1] op_sel_hi:[1,0]
	v_max_f32_e32 v62, 0, v62
	v_max_f32_e32 v58, 0, v58
	v_max_f32_e32 v63, 0, v63
	v_max_f32_e32 v59, 0, v59
	v_max_f32_e32 v64, 0, v64
	v_max_f32_e32 v60, 0, v60
	v_max_f32_e32 v65, 0, v65
	v_max_f32_e32 v61, 0, v61
	v_max_f32_e32 v54, 0, v54
	v_max_f32_e32 v50, 0, v50
	v_max_f32_e32 v55, 0, v55
	v_max_f32_e32 v51, 0, v51
	v_max_f32_e32 v56, 0, v56
	v_max_f32_e32 v52, 0, v52
	v_max_f32_e32 v57, 0, v57
	v_max_f32_e32 v53, 0, v53
	v_pk_mul_f32 v[62:63], v[62:63], v[62:63]
	v_pk_mul_f32 v[58:59], v[58:59], v[58:59]
	v_pk_mul_f32 v[64:65], v[64:65], v[64:65]
	v_pk_mul_f32 v[60:61], v[60:61], v[60:61]
	v_pk_mul_f32 v[54:55], v[54:55], v[54:55]
	v_pk_mul_f32 v[68:69], v[50:51], v[50:51]
; DEVI u32x4 pack8(const f32x4 a, const f32x4 b) { u32x4 w; w.x = cvtpk(a[0], a[1]); w.y = cvtpk(a[2], a[3]); w.z = cvtpk(b[0], b[1]); w.w = cvtpk(b[2], b[3]); return w; }
; #define ROWLOOP _Pragma("unroll") for (int ai = 0; ai < 2; ++ai) _Pragma("unroll") for (int m = 0; m < 4; ++m)
;     DEVI void operator()(AccRef acc, const Unit& u, int wr, int wc, int fr, int fq) const {
;     ...
;         ROWLOOP {
;             const int row = ROWOF(u);
;             const float r = rsqrtf(ssq[row] * (1.f / 1024.f) + EPSF);
; #pragma unroll
;             for (int bj = 0; bj < 2; ++bj) {
;                 f32x4 a = acc[ai][bj][m][0] * r, b = acc[ai][bj][m][1] * r;
; #pragma unroll
;                 for (int j = 0; j < 4; ++j) { const float x = fmaxf(a[j], 0.f), y = fmaxf(b[j], 0.f); a[j] = x * x; b[j] = y * y; }
;                 *(u32x4*)(ah + (size_t)row * DFF + u.pn * 256 + bj * 128 + wc * 32 + 8 * fq) = pack8(a, b);
;             }
;         }
;     }
	v_pk_mul_f32 v[56:57], v[56:57], v[56:57]
	v_pk_mul_f32 v[70:71], v[52:53], v[52:53]
	v_cvt_pk_bf16_f32 v50, v62, v63
	v_cvt_pk_bf16_f32 v51, v64, v65
	v_cvt_pk_bf16_f32 v52, v58, v59
	v_cvt_pk_bf16_f32 v53, v60, v61
	v_cvt_pk_bf16_f32 v54, v54, v55
	v_cvt_pk_bf16_f32 v55, v56, v57
	v_cvt_pk_bf16_f32 v56, v68, v69
	v_cvt_pk_bf16_f32 v57, v70, v71
	global_store_dwordx4 v[66:67], v[50:53], off
	global_store_dwordx4 v[66:67], v[54:57], off offset:256
	s_nop 0
	v_add_u32_e32 v50, 0x90, v142
	v_fmamk_f32 v0, v160, 0x3a800000, v233
	v_mul_f32_e32 v51, 0x4b800000, v0
	v_cmp_gt_f32_e32 vcc, s25, v0
	s_nop 1
	v_cndmask_b32_e32 v0, v0, v51, vcc
	v_rsq_f32_e32 v0, v0
	v_ashrrev_i32_e32 v51, 31, v50
	v_lshlrev_b64 v[50:51], 13, v[50:51]
	v_lshl_add_u64 v[50:51], v[144:145], 0, v[50:51]
	v_mul_f32_e32 v52, 0x45800000, v0
	v_cndmask_b32_e32 v0, v0, v52, vcc
	v_pk_mul_f32 v[48:49], v[48:49], v[0:1] op_sel_hi:[1,0]
	v_pk_mul_f32 v[46:47], v[46:47], v[0:1] op_sel_hi:[1,0]
	v_pk_mul_f32 v[44:45], v[44:45], v[0:1] op_sel_hi:[1,0]
	v_pk_mul_f32 v[42:43], v[42:43], v[0:1] op_sel_hi:[1,0]
	v_pk_mul_f32 v[40:41], v[40:41], v[0:1] op_sel_hi:[1,0]
	v_pk_mul_f32 v[38:39], v[38:39], v[0:1] op_sel_hi:[1,0]
	v_pk_mul_f32 v[36:37], v[36:37], v[0:1] op_sel_hi:[1,0]
	v_pk_mul_f32 v[34:35], v[34:35], v[0:1] op_sel_hi:[1,0]
	v_max_f32_e32 v46, 0, v46
	v_max_f32_e32 v42, 0, v42
	v_max_f32_e32 v47, 0, v47
	v_max_f32_e32 v43, 0, v43
	v_max_f32_e32 v48, 0, v48
	v_max_f32_e32 v44, 0, v44
	v_max_f32_e32 v49, 0, v49
	v_max_f32_e32 v45, 0, v45
	v_max_f32_e32 v38, 0, v38
	v_max_f32_e32 v34, 0, v34
	v_max_f32_e32 v39, 0, v39
	v_max_f32_e32 v35, 0, v35
	v_max_f32_e32 v40, 0, v40
	v_max_f32_e32 v36, 0, v36
	v_max_f32_e32 v41, 0, v41
	v_max_f32_e32 v37, 0, v37
	v_pk_mul_f32 v[46:47], v[46:47], v[46:47]
	v_pk_mul_f32 v[42:43], v[42:43], v[42:43]
	v_pk_mul_f32 v[48:49], v[48:49], v[48:49]
	v_pk_mul_f32 v[44:45], v[44:45], v[44:45]
	v_pk_mul_f32 v[38:39], v[38:39], v[38:39]
	v_pk_mul_f32 v[52:53], v[34:35], v[34:35]
	v_pk_mul_f32 v[40:41], v[40:41], v[40:41]
	v_pk_mul_f32 v[54:55], v[36:37], v[36:37]
	v_cvt_pk_bf16_f32 v34, v46, v47
	v_cvt_pk_bf16_f32 v35, v48, v49
	v_cvt_pk_bf16_f32 v36, v42, v43
	v_cvt_pk_bf16_f32 v37, v44, v45
	v_cvt_pk_bf16_f32 v38, v38, v39
	v_cvt_pk_bf16_f32 v39, v40, v41
	v_cvt_pk_bf16_f32 v40, v52, v53
	v_cvt_pk_bf16_f32 v41, v54, v55
	global_store_dwordx4 v[50:51], v[34:37], off
	global_store_dwordx4 v[50:51], v[38:41], off offset:256
	s_nop 0
	v_add_u32_e32 v34, 0xa0, v142
	v_fmamk_f32 v0, v161, 0x3a800000, v233
	v_mul_f32_e32 v35, 0x4b800000, v0
	v_cmp_gt_f32_e32 vcc, s25, v0
	s_nop 1
	v_cndmask_b32_e32 v0, v0, v35, vcc
	v_rsq_f32_e32 v0, v0
	v_ashrrev_i32_e32 v35, 31, v34
	v_lshlrev_b64 v[34:35], 13, v[34:35]
	v_lshl_add_u64 v[34:35], v[144:145], 0, v[34:35]
	v_mul_f32_e32 v36, 0x45800000, v0
	v_cndmask_b32_e32 v0, v0, v36, vcc
	v_pk_mul_f32 v[32:33], v[32:33], v[0:1] op_sel_hi:[1,0]
	v_pk_mul_f32 v[30:31], v[30:31], v[0:1] op_sel_hi:[1,0]
	v_pk_mul_f32 v[28:29], v[28:29], v[0:1] op_sel_hi:[1,0]
	v_pk_mul_f32 v[26:27], v[26:27], v[0:1] op_sel_hi:[1,0]
	v_pk_mul_f32 v[24:25], v[24:25], v[0:1] op_sel_hi:[1,0]
	v_pk_mul_f32 v[22:23], v[22:23], v[0:1] op_sel_hi:[1,0]
	v_pk_mul_f32 v[20:21], v[20:21], v[0:1] op_sel_hi:[1,0]
	v_pk_mul_f32 v[18:19], v[18:19], v[0:1] op_sel_hi:[1,0]
	v_max_f32_e32 v30, 0, v30
	v_max_f32_e32 v26, 0, v26
	v_max_f32_e32 v31, 0, v31
	v_max_f32_e32 v27, 0, v27
	v_max_f32_e32 v32, 0, v32
	v_max_f32_e32 v28, 0, v28
	v_max_f32_e32 v33, 0, v33
	v_max_f32_e32 v29, 0, v29
	v_max_f32_e32 v22, 0, v22
	v_max_f32_e32 v18, 0, v18
	v_max_f32_e32 v23, 0, v23
	v_max_f32_e32 v19, 0, v19
	v_max_f32_e32 v24, 0, v24
	v_max_f32_e32 v20, 0, v20
	v_max_f32_e32 v25, 0, v25
	v_max_f32_e32 v21, 0, v21
	v_pk_mul_f32 v[30:31], v[30:31], v[30:31]
	v_pk_mul_f32 v[26:27], v[26:27], v[26:27]
	v_pk_mul_f32 v[32:33], v[32:33], v[32:33]
	v_pk_mul_f32 v[28:29], v[28:29], v[28:29]
	v_pk_mul_f32 v[22:23], v[22:23], v[22:23]
	v_pk_mul_f32 v[36:37], v[18:19], v[18:19]
	v_pk_mul_f32 v[24:25], v[24:25], v[24:25]
	v_pk_mul_f32 v[38:39], v[20:21], v[20:21]
	v_cvt_pk_bf16_f32 v18, v30, v31
	v_cvt_pk_bf16_f32 v19, v32, v33
	v_cvt_pk_bf16_f32 v20, v26, v27
	v_cvt_pk_bf16_f32 v21, v28, v29
	v_cvt_pk_bf16_f32 v22, v22, v23
	v_cvt_pk_bf16_f32 v23, v24, v25
	v_cvt_pk_bf16_f32 v24, v36, v37
	v_cvt_pk_bf16_f32 v25, v38, v39
	global_store_dwordx4 v[34:35], v[18:21], off
	global_store_dwordx4 v[34:35], v[22:25], off offset:256
	s_nop 0
	v_add_u32_e32 v18, 0xb0, v142
	v_ashrrev_i32_e32 v19, 31, v18
	v_lshlrev_b64 v[18:19], 13, v[18:19]
	s_andn2_b64 vcc, exec, s[2:3]
	v_lshl_add_u64 v[18:19], v[144:145], 0, v[18:19]
	s_mov_b64 s[2:3], -1
	v_fmamk_f32 v0, v162, 0x3a800000, v233
	v_mul_f32_e32 v20, 0x4b800000, v0
	v_cmp_gt_f32_e64 s[4:5], s25, v0
	s_nop 1
	v_cndmask_b32_e64 v0, v0, v20, s[4:5]
	v_rsq_f32_e32 v0, v0
	s_nop 0
	v_mul_f32_e32 v20, 0x45800000, v0
	v_cndmask_b32_e64 v0, v0, v20, s[4:5]
	v_pk_mul_f32 v[16:17], v[16:17], v[0:1] op_sel_hi:[1,0]
	v_pk_mul_f32 v[14:15], v[14:15], v[0:1] op_sel_hi:[1,0]
	v_pk_mul_f32 v[12:13], v[12:13], v[0:1] op_sel_hi:[1,0]
	v_pk_mul_f32 v[10:11], v[10:11], v[0:1] op_sel_hi:[1,0]
	v_pk_mul_f32 v[8:9], v[8:9], v[0:1] op_sel_hi:[1,0]
	v_pk_mul_f32 v[6:7], v[6:7], v[0:1] op_sel_hi:[1,0]
	v_pk_mul_f32 v[4:5], v[4:5], v[0:1] op_sel_hi:[1,0]
	v_pk_mul_f32 v[2:3], v[2:3], v[0:1] op_sel_hi:[1,0]
	v_max_f32_e32 v14, 0, v14
	v_max_f32_e32 v10, 0, v10
	v_max_f32_e32 v15, 0, v15
	v_max_f32_e32 v11, 0, v11
	v_max_f32_e32 v16, 0, v16
	v_max_f32_e32 v12, 0, v12
	v_max_f32_e32 v17, 0, v17
	v_max_f32_e32 v13, 0, v13
	v_max_f32_e32 v6, 0, v6
	v_max_f32_e32 v2, 0, v2
	v_max_f32_e32 v7, 0, v7
	v_max_f32_e32 v3, 0, v3
	v_max_f32_e32 v8, 0, v8
	v_max_f32_e32 v4, 0, v4
	v_max_f32_e32 v9, 0, v9
	v_max_f32_e32 v5, 0, v5
	v_pk_mul_f32 v[14:15], v[14:15], v[14:15]
	v_pk_mul_f32 v[10:11], v[10:11], v[10:11]
	v_pk_mul_f32 v[16:17], v[16:17], v[16:17]
	v_pk_mul_f32 v[12:13], v[12:13], v[12:13]
	v_pk_mul_f32 v[6:7], v[6:7], v[6:7]
	v_pk_mul_f32 v[20:21], v[2:3], v[2:3]
	v_pk_mul_f32 v[8:9], v[8:9], v[8:9]
	v_pk_mul_f32 v[22:23], v[4:5], v[4:5]
	v_cvt_pk_bf16_f32 v2, v14, v15
	v_cvt_pk_bf16_f32 v3, v16, v17
	v_cvt_pk_bf16_f32 v4, v10, v11
	v_cvt_pk_bf16_f32 v5, v12, v13
	v_cvt_pk_bf16_f32 v6, v6, v7
	v_cvt_pk_bf16_f32 v7, v8, v9
	v_cvt_pk_bf16_f32 v8, v20, v21
	v_cvt_pk_bf16_f32 v9, v22, v23
	global_store_dwordx4 v[18:19], v[2:5], off
	global_store_dwordx4 v[18:19], v[6:9], off offset:256
	s_cbranch_vccnz .LBB0_1616
	s_andn2_b64 vcc, exec, s[6:7]
	s_cbranch_vccnz .LBB0_1615
	s_barrier
	s_branch .LBB0_1615
